# post_attn cache conversion: one (row, kv head) per wave over all 2048 waves, hand-written body with 2 overlapped loads instead of a 7-round-trip extra iteration on 512 waves
# speedup vs baseline: 1.0103x; 1.0103x over previous
.LBB0_990:
	s_andn2_b64 vcc, exec, s[0:1]
	s_cbranch_vccnz .LBB0_1043
	v_mov_b32_e32 v16, v192
	v_mov_b32_e32 v0, v192
	s_add_u32 s18, s92, 0x10c40000
	v_ashrrev_i32_e32 v0, 6, v0
	v_add_u32_e32 v32, s73, v0
	s_movk_i32 s0, 0x4800
	s_addc_u32 s19, s93, 0
	v_cmp_gt_i32_e32 vcc, s0, v32
	s_and_saveexec_b64 s[20:21], vcc
	s_cbranch_execz .LBB0_1036
	v_lshlrev_b32_e32 v0, 5, v16
	v_readlane_b32 s44, v253, 40
	v_and_b32_e32 v12, 0xe0, v0
	v_readlane_b32 s58, v253, 54
	v_readlane_b32 s59, v253, 55
	s_nop 4
	global_load_dwordx4 v[0:3], v12, s[58:59] offset:16
	global_load_dwordx4 v[4:7], v12, s[58:59]
	global_load_dwordx4 v[8:11], v12, s[40:41] offset:16
	s_nop 0
	global_load_dwordx4 v[12:15], v12, s[40:41]
	v_lshlrev_b32_e32 v17, 3, v16
	v_and_b32_e32 v20, 4, v16
	v_and_b32_e32 v17, 8, v17
	v_cmp_eq_u32_e64 s[8:9], 0, v20
	v_cvt_f32_ubyte0_e32 v20, v17
	v_mul_f32_e32 v20, 0xbf549a78, v20
	v_exp_f32_e32 v35, v20
	v_or_b32_e32 v20, 1, v17
	v_cvt_f32_ubyte0_e32 v20, v20
	v_mul_f32_e32 v20, 0xbf549a78, v20
	v_exp_f32_e32 v66, v20
	v_or_b32_e32 v20, 2, v17
	v_cvt_f32_ubyte0_e32 v20, v20
	v_mul_f32_e32 v20, 0xbf549a78, v20
	v_exp_f32_e32 v67, v20
	v_or_b32_e32 v20, 3, v17
	v_cvt_f32_ubyte0_e32 v20, v20
	v_mul_f32_e32 v20, 0xbf549a78, v20
	v_exp_f32_e32 v68, v20
	v_or_b32_e32 v20, 4, v17
	v_cvt_f32_ubyte0_e32 v20, v20
	v_mul_f32_e32 v20, 0xbf549a78, v20
	v_exp_f32_e32 v69, v20
	v_or_b32_e32 v20, 5, v17
	v_cvt_f32_ubyte0_e32 v20, v20
	v_mul_f32_e32 v20, 0xbf549a78, v20
	v_exp_f32_e32 v70, v20
	v_or_b32_e32 v20, 6, v17
	v_or_b32_e32 v17, 7, v17
	v_cvt_f32_ubyte0_e32 v20, v20
	v_cvt_f32_ubyte0_e32 v17, v17
	v_and_b32_e32 v34, 63, v16
	v_readlane_b32 s4, v254, 41
	v_mul_f32_e32 v20, 0xbf549a78, v20
	v_mul_f32_e32 v17, 0xbf549a78, v17
	v_lshlrev_b32_e32 v18, 1, v34
	v_mov_b32_e32 v19, v112
	v_readlane_b32 s5, v254, 42
	v_readlane_b32 s0, v254, 39
	v_exp_f32_e32 v71, v20
	v_exp_f32_e32 v72, v17
	v_and_b32_e32 v16, 2, v16
	v_lshl_add_u64 v[36:37], s[4:5], 0, v[18:19]
	v_lshlrev_b32_e32 v18, 4, v34
	v_readlane_b32 s1, v254, 40
	v_cmp_eq_u32_e64 s[10:11], 0, v16
	v_lshlrev_b32_e32 v16, 5, v34
	v_mov_b32_e32 v17, v112
	v_lshl_add_u64 v[38:39], s[0:1], 0, v[18:19]
	v_lshl_add_u64 v[40:41], s[62:63], 0, v[16:17]
	s_mov_b64 s[0:1], 0x4000000
	s_add_u32 s22, s92, 0x380000
	v_cmp_eq_u32_e64 s[6:7], 0, v34
	v_cmp_lt_u32_e64 s[12:13], 31, v34
	v_lshl_add_u64 v[42:43], v[40:41], 0, s[0:1]
	v_lshl_add_u64 v[44:45], s[4:5], 0, v[18:19]
	s_addc_u32 s23, s93, 0
	s_mov_b64 s[24:25], 0
	v_readlane_b32 s45, v253, 41
	v_readlane_b32 s46, v253, 42
	v_readlane_b32 s47, v253, 43
	v_readlane_b32 s48, v253, 44
	v_readlane_b32 s49, v253, 45
	v_readlane_b32 s50, v253, 46
	v_readlane_b32 s51, v253, 47
	v_readlane_b32 s52, v253, 48
	v_readlane_b32 s53, v253, 49
	v_readlane_b32 s54, v253, 50
	v_readlane_b32 s55, v253, 51
	v_readlane_b32 s56, v253, 52
	v_readlane_b32 s57, v253, 53
	s_branch .LBB0_996

.LBB0_995:
	s_or_b64 exec, exec, s[26:27]
	v_readlane_b32 s0, v253, 3
	v_readlane_b32 s1, v253, 4
	s_nop 0
	v_add_u32_e32 v32, s0, v32
	s_movk_i32 s0, 0x47ff
	v_cmp_lt_i32_e32 vcc, s0, v32
	s_or_b64 s[24:25], vcc, s[24:25]
	s_andn2_b64 exec, exec, s[24:25]
	s_cbranch_execz .LBB0_1036
.LBB0_996:
	s_movk_i32 s0, 0x3fff
	v_cmp_lt_i32_e32 vcc, s0, v32
	s_and_saveexec_b64 s[0:1], vcc
	s_xor_b64 s[14:15], exec, s[0:1]
	s_cbranch_execz .LBB0_1018
	v_add_u32_e32 v22, 0xffffc000, v32
	v_readlane_b32 s48, v253, 28
	v_readlane_b32 s49, v253, 29
	v_readlane_b32 s50, v253, 30
	v_readlane_b32 s51, v253, 31
	v_readlane_b32 s44, v253, 24
	v_readlane_b32 s45, v253, 25
	v_readlane_b32 s46, v253, 26
	v_readlane_b32 s47, v253, 27
	v_readlane_b32 s52, v253, 32
	v_readlane_b32 s53, v253, 33
	v_readlane_b32 s54, v253, 34
	v_readlane_b32 s55, v253, 35
	v_readlane_b32 s56, v253, 36
	v_readlane_b32 s57, v253, 37
	v_readlane_b32 s58, v253, 38
	v_readlane_b32 s59, v253, 39
	v_lshl_or_b32 v20, v22, 6, v34
	v_mov_b32_e32 v21, v112
	v_lshl_add_u64 v[18:19], v[20:21], 2, s[48:49]
	v_lshl_add_u64 v[20:21], v[20:21], 2, s[50:51]
	global_load_dword v23, v[18:19], off
	global_load_dword v28, v[20:21], off
	v_lshrrev_b32_e32 v16, 2, v22
	v_and_b32_e32 v24, 3, v22
	v_lshrrev_b32_e32 v17, 8, v16
	v_mul_u32_u24_e32 v17, 0x1100, v17
	v_and_b32_e32 v25, 0xff, v16
	v_or_b32_e32 v16, v17, v25
	v_mov_b32_e32 v17, v112
	v_lshlrev_b64 v[16:17], 9, v[16:17]
	v_lshl_add_u32 v16, v24, 7, v16
	v_lshl_add_u64 v[16:17], v[36:37], 0, v[16:17]
	v_lshlrev_b32_e32 v26, 1, v25
	v_mov_b32_e32 v27, v112
	v_lshl_add_u64 v[26:27], s[18:19], 0, v[26:27]
	v_lshrrev_b32_e32 v29, 10, v22
	v_lshlrev_b32_e32 v29, 8, v29
	v_lshl_or_b32 v29, v24, 6, v29
	v_or_b32_e32 v29, v29, v34
	s_movk_i32 s0, 0x2200
	v_mad_u64_u32 v[26:27], s[0:1], v29, s0, v[26:27]
	v_lshlrev_b32_e32 v31, 2, v192
	v_bitop3_b32 v25, v31, s33, v203 bitop3:0x6c
	s_waitcnt vmcnt(1)
	v_cvt_pk_bf16_f32 v23, v23, s0
	global_store_short v[16:17], v23, off
	v_lshlrev_b32_e32 v23, 16, v23
	v_mul_f32_e32 v30, v23, v23
	ds_bpermute_b32 v24, v25, v30
	v_bitop3_b32 v25, v31, 64, v203 bitop3:0x6c
	s_waitcnt lgkmcnt(0)
	v_add_f32_e32 v30, v30, v24
	ds_bpermute_b32 v24, v25, v30
	v_bitop3_b32 v25, v31, 32, v203 bitop3:0x6c
	s_waitcnt lgkmcnt(0)
	v_add_f32_e32 v30, v30, v24
	ds_bpermute_b32 v24, v25, v30
	v_bitop3_b32 v25, v31, 16, v203 bitop3:0x6c
	s_waitcnt lgkmcnt(0)
	v_add_f32_e32 v30, v30, v24
	ds_bpermute_b32 v24, v25, v30
	v_bitop3_b32 v25, v31, 8, v203 bitop3:0x6c
	s_waitcnt lgkmcnt(0)
	v_add_f32_e32 v30, v30, v24
	ds_bpermute_b32 v24, v25, v30
	v_bitop3_b32 v25, v31, 4, v203 bitop3:0x6c
	s_waitcnt lgkmcnt(0)
	v_add_f32_e32 v30, v30, v24
	ds_bpermute_b32 v24, v25, v30
	s_waitcnt lgkmcnt(0)
	v_add_f32_e32 v30, v30, v24
	s_waitcnt vmcnt(1)
	v_cvt_pk_bf16_f32 v28, v28, s0
	global_store_short v[26:27], v28, off
	v_cmp_eq_u32_e32 vcc, 0, v34
	s_and_saveexec_b64 s[0:1], vcc
	global_atomic_umax v112, v30, s[22:23]
	s_or_b64 exec, exec, s[0:1]
